# code placement: all code after the first dead gap shifted by 32 bytes (8 unreachable s_nop after an unconditional branch)
# speedup vs baseline: 1.0022x; 1.0022x over previous
; __global__ void __launch_bounds__(NWAVES * 64, 2) mega_fwd(Args args) {
;     ...
;     unsigned char* ws = args.ws;
;     gu32* ctl = (gu32*)(ws + WS_CTL);
;     const float* x = args.in[0]; const float* g_mix = args.in[1]; const float* w_in = args.in[2];
;     const float* lq1 = args.in[3]; const float* lk1 = args.in[4]; const float* lq2 = args.in[5]; const float* lk2 = args.in[6];
;     const float* subg = args.in[7]; const float* relb = args.in[8]; const float* w_out = args.in[9]; const float* g_mlp = args.in[10];
;     const float* w_up = args.in[11]; const float* w_dn = args.in[12]; const float* g_fin = args.in[13];
;     float* out = args.out;
;     bf16* PROJ = (bf16*)(ws + WS_PROJ); bf16* KBI = (bf16*)(ws + WS_KB); bf16* VBI = (bf16*)(ws + WS_VB); bf16* X1B = (bf16*)(ws + WS_X1B); bf16* UB = (bf16*)(ws + WS_U); bf16* XN = (bf16*)(ws + WS_XN); bf16* MIX = (bf16*)(ws + WS_MIX);
;     bf16* WIN = (bf16*)(ws + WS_WIN); bf16* WOUT = (bf16*)(ws + WS_WOUT); bf16* WUP = (bf16*)(ws + WS_WUP); bf16* WDN = (bf16*)(ws + WS_WDN);
;     f32x2* ROT = (f32x2*)(ws + WS_ROT);
;     float* SSQ0 = (float*)(ws + WS_CTL + CTL_SSQ0); float* SSQ1 = (float*)(ws + WS_CTL + CTL_SSQ1); float* SSQ2 = (float*)(ws + WS_CTL + CTL_SSQ2);
;     for (int u = tid; u < (LDS_BYTES - LDSCTL_OFF) / 4; u += NWAVES * 64) ((LAS unsigned*)(ldsl + LDSCTL_OFF))[u] = 0u;
;     __syncthreads();
;     XcdBarrier bar; bar.bar = (unsigned*)(ctl + CW_BAR); bar.x = 0; bar.st = nullptr;
;     if (N_LAUNCHES != PER_PHASE) bar = xcd_barrier_post((unsigned*)(ctl + CW_BAR), MISC + 8);
;     if (N_LAUNCHES != PER_PHASE && G == 256 && tid == 0) { (void)xb_add((unsigned*)(ctl + CW_GRP + 64 * (vcu >> 3) + 1), XB_CENSUS(bar.x)); (void)xb_add((unsigned*)(ctl + CW_TEAM + 64 * (vcu >> 5) + 1), XB_CENSUS(bar.x)); }
;     ...
;     unsigned gtarget = 0;
;     const bool PANEL_NOINV = ((vcu >> 3) != 21) && ((vcu >> 3) != 31);
;     ...
;     const int lo = args.ph_lo, hi = args.ph_hi;
;     ...
;     if (IN(0)) {
;         LAS float* scr = (LAS float*)(ldsl + RING_OFF + wave * 16896);
;         const int gw = vcu * NWAVES + wave, NGW = G * NWAVES;
;         constexpr int I_IN = (DM / 64) * (NIN / 64), I_OUT = (DM / 64) * (DM / 64), I_UP = (DM / 64) * (DFF / 64), I_DN = (DFF / 64) * (DM / 64);
;         const int NITEMS = (G == 256) ? I_IN : I_IN + I_OUT + I_UP + I_DN;
;         auto mk = [&](int it) -> TItem {
;             int r = it;
.LBB0_12:
	v_writelane_b32 v242, s16, 12
	s_nop 1
	v_writelane_b32 v242, s17, 13
	v_writelane_b32 v242, s2, 14
	v_writelane_b32 v242, s14, 15
	v_writelane_b32 v242, s12, 16
	s_nop 1
	v_writelane_b32 v242, s13, 17
	s_or_b64 exec, exec, s[4:5]
	s_add_u32 s90, s70, 0x6000000
	s_addc_u32 s91, s71, 0
	s_add_u32 s92, s70, 0x8000000
	s_addc_u32 s93, s71, 0
	s_add_u32 s94, s70, 0xe200000
	s_addc_u32 s95, s71, 0
	s_add_u32 s84, s70, 0xa000000
	s_addc_u32 s85, s71, 0
	s_add_u32 s74, s70, 0xc000000
	s_load_dwordx16 s[8:23], s[0:1], 0x0
	s_addc_u32 s75, s71, 0
	s_lshr_b32 s0, s24, 6
	v_writelane_b32 v242, s0, 18
	v_and_b32_e32 v194, 63, v0
	v_readlane_b32 s4, v242, 6
	v_readlane_b32 s5, v242, 7
	s_cmp_lt_i32 s4, 1
	s_cselect_b64 s[0:1], -1, 0
	s_cmp_gt_i32 s5, 0
	s_cselect_b64 s[2:3], -1, 0
	s_and_b64 s[0:1], s[0:1], s[2:3]
	s_andn2_b64 vcc, exec, s[0:1]
	s_cbranch_vccnz .LBB0_155
	s_lshl_b32 s0, s76, 3
	v_readlane_b32 s1, v242, 18
	s_add_i32 s6, s0, s1
	v_readlane_b32 s0, v242, 12
	v_readlane_b32 s1, v242, 13
	s_movk_i32 s2, 0xc00
	s_and_b64 s[0:1], s[0:1], exec
	s_cselect_b32 s3, s2, 0x3000
	s_cmp_lt_i32 s6, s3
	s_cselect_b64 s[0:1], -1, 0
	s_cmp_ge_i32 s6, s3
	s_cbranch_scc1 .LBB0_26
	s_cmpk_lt_i32 s6, 0xc00
	s_cbranch_scc1 .LBB0_18
	s_cmpk_gt_u32 s6, 0xfff
	s_cbranch_scc0 .LBB0_19
	s_cmpk_gt_u32 s6, 0x1fff
	s_cbranch_scc0 .LBB0_20
	s_add_i32 s2, s6, 0xffffe000
	s_mov_b64 s[24:25], 0
	s_mov_b64 s[4:5], s[64:65]
	s_branch .LBB0_21
	s_nop 0
	s_nop 0
	s_nop 0
	s_nop 0
	s_nop 0
	s_nop 0
	s_nop 0
	s_nop 0
